# prep phase: nt (streaming) hint on the read-once f32 weight/input loads of the three f32-to-bf16 conversion loops
# speedup vs baseline: 1.0121x; 1.0029x over previous
; __device__ __forceinline__ unsigned cvt_pk_bf16(float lo, float hi) { const f32x2_t v = {lo, hi}; const bf16x2_t b = __builtin_convertvector(v, bf16x2_t); return __builtin_bit_cast(unsigned, b); }
; __device__ __forceinline__ unsigned cvt_pk_f16(float lo, float hi) { const f32x2 v = {lo, hi}; const h16x2_t h = __builtin_convertvector(v, h16x2_t); return __builtin_bit_cast(unsigned, h); }
; __device__ __forceinline__ u64 ssq_fix(float s) { return (u64)__float2ull_rn(s * 16777216.0f); }
; __device__ __forceinline__ void rows_to_bf16(const float* X, bf16_t* XB, bf16_t* X16, u64* ssq, int rows, int gw, int nw) {
;     int tid_ = threadIdx.x; asm volatile("" : "+v"(tid_)); asm volatile("" : "+v"(gw));
;     const int lane = tid_ & 63;
;     for (int r = gw; r < rows; r += nw) {
;         const float* xr = X + (size_t)r * D; bf16_t* br = XB + (size_t)r * D; float ss = 0.f;
; #pragma unroll
;         for (int i = 0; i < 8; ++i) {
;             const f32x4 v = *(const f32x4*)(xr + (i * 64 + lane) * 4);
;             ss += v[0] * v[0] + v[1] * v[1] + v[2] * v[2] + v[3] * v[3];
;             u32x2 w; w.x = cvt_pk_bf16(v[0], v[1]); w.y = cvt_pk_bf16(v[2], v[3]);
;             *(u32x2*)(br + (i * 64 + lane) * 4) = w;
;             if (X16) { u32x2 hq; hq.x = cvt_pk_f16(v[0], v[1]); hq.y = cvt_pk_f16(v[2], v[3]); *(u32x2*)(X16 + (size_t)r * D + (i * 64 + lane) * 4) = hq; }
;         }
;         ss = wave_sum(ss);
;         if (lane == 0) ssq[r] = ssq_fix(ss);
;     }
.LBB0_953:
	s_waitcnt lgkmcnt(0)
	global_load_dwordx4 v[22:25], v[8:9], off offset:-4096 nt
	global_load_dwordx4 v[58:61], v[8:9], off offset:-3072 nt
	global_load_dwordx4 v[62:65], v[8:9], off offset:-2048 nt
	global_load_dwordx4 v[66:69], v[8:9], off offset:-1024 nt
	global_load_dwordx4 v[70:73], v[8:9], off nt
	global_load_dwordx4 v[74:77], v[8:9], off offset:1024 nt
	global_load_dwordx4 v[78:81], v[8:9], off offset:2048 nt
	global_load_dwordx4 v[82:85], v[8:9], off offset:3072 nt
	v_lshl_add_u64 v[26:27], s[22:23], 0, v[6:7]
	s_mov_b32 s2, 0xda29000
	s_waitcnt vmcnt(19)
	v_add_co_u32_e32 v54, vcc, s2, v26
	s_mov_b32 s2, 0x367a9000
	s_nop 0
	v_addc_co_u32_e32 v55, vcc, 0, v27, vcc
	s_waitcnt vmcnt(18)
	v_add_co_u32_e32 v56, vcc, s2, v26
	s_waitcnt vmcnt(7)
	v_cvt_pk_bf16_f32 v26, v22, v23
	v_addc_co_u32_e32 v57, vcc, 0, v27, vcc
	v_cvt_pk_bf16_f32 v27, v24, v25
	v_cvt_pk_f16_f32 v28, v22, v23
	v_cvt_pk_f16_f32 v29, v24, v25
	global_store_dwordx2 v[54:55], v[26:27], off
	global_store_dwordx2 v[56:57], v[28:29], off
	s_waitcnt vmcnt(8)
	s_nop 1
	v_mov_b64_e32 v[26:27], v[58:59]
	v_mov_b64_e32 v[28:29], v[60:61]
	v_mul_f32_e32 v3, v23, v23
	v_fmac_f32_e32 v3, v22, v22
	v_fmac_f32_e32 v3, v24, v24
	v_fmac_f32_e32 v3, v25, v25
	v_cvt_pk_bf16_f32 v30, v26, v27
	v_cvt_pk_bf16_f32 v31, v28, v29
	v_cvt_pk_f16_f32 v32, v26, v27
	v_cvt_pk_f16_f32 v33, v28, v29
	global_store_dwordx2 v[54:55], v[30:31], off offset:512
	global_store_dwordx2 v[56:57], v[32:33], off offset:512
	s_waitcnt vmcnt(9)
	s_nop 1
	v_mov_b64_e32 v[30:31], v[62:63]
	v_mov_b64_e32 v[32:33], v[64:65]
	v_mul_f32_e32 v22, v27, v27
	v_fmac_f32_e32 v22, v26, v26
	v_fmac_f32_e32 v22, v28, v28
	v_fmac_f32_e32 v22, v29, v29
	v_add_f32_e32 v3, v3, v22
	v_cvt_pk_bf16_f32 v34, v30, v31
	v_cvt_pk_bf16_f32 v35, v32, v33
	v_cvt_pk_f16_f32 v36, v30, v31
	v_cvt_pk_f16_f32 v37, v32, v33
	global_store_dwordx2 v[54:55], v[34:35], off offset:1024
	global_store_dwordx2 v[56:57], v[36:37], off offset:1024
	s_waitcnt vmcnt(10)
	s_nop 1
	v_mov_b64_e32 v[34:35], v[66:67]
	v_mov_b64_e32 v[36:37], v[68:69]
	v_mul_f32_e32 v22, v31, v31
	v_fmac_f32_e32 v22, v30, v30
	v_fmac_f32_e32 v22, v32, v32
	v_fmac_f32_e32 v22, v33, v33
	v_add_f32_e32 v3, v3, v22
	v_cvt_pk_bf16_f32 v38, v34, v35
	v_cvt_pk_bf16_f32 v39, v36, v37
	v_cvt_pk_f16_f32 v40, v34, v35
	v_cvt_pk_f16_f32 v41, v36, v37
	global_store_dwordx2 v[54:55], v[38:39], off offset:1536
	global_store_dwordx2 v[56:57], v[40:41], off offset:1536
	s_waitcnt vmcnt(11)
	s_nop 1
	v_mov_b64_e32 v[38:39], v[70:71]
	v_mov_b64_e32 v[40:41], v[72:73]
	v_mul_f32_e32 v22, v35, v35
	v_fmac_f32_e32 v22, v34, v34
	v_fmac_f32_e32 v22, v36, v36
	v_fmac_f32_e32 v22, v37, v37
	v_add_f32_e32 v3, v3, v22
	v_cvt_pk_bf16_f32 v42, v38, v39
	v_cvt_pk_bf16_f32 v43, v40, v41
	v_cvt_pk_f16_f32 v44, v38, v39
	v_cvt_pk_f16_f32 v45, v40, v41
	global_store_dwordx2 v[54:55], v[42:43], off offset:2048
	global_store_dwordx2 v[56:57], v[44:45], off offset:2048
	s_waitcnt vmcnt(12)
	s_nop 1
	v_mov_b64_e32 v[42:43], v[74:75]
	v_mov_b64_e32 v[44:45], v[76:77]
	v_mul_f32_e32 v22, v39, v39
	v_fmac_f32_e32 v22, v38, v38
	v_fmac_f32_e32 v22, v40, v40
	v_fmac_f32_e32 v22, v41, v41
	v_add_f32_e32 v3, v3, v22
	v_cvt_pk_bf16_f32 v46, v42, v43
	v_cvt_pk_bf16_f32 v47, v44, v45
	v_cvt_pk_f16_f32 v48, v42, v43
	v_cvt_pk_f16_f32 v49, v44, v45
	global_store_dwordx2 v[54:55], v[46:47], off offset:2560
	global_store_dwordx2 v[56:57], v[48:49], off offset:2560
	s_waitcnt vmcnt(13)
	s_nop 1
	v_mov_b64_e32 v[46:47], v[78:79]
	v_mov_b64_e32 v[48:49], v[80:81]
	v_mul_f32_e32 v22, v43, v43
	v_fmac_f32_e32 v22, v42, v42
	v_fmac_f32_e32 v22, v44, v44
	v_fmac_f32_e32 v22, v45, v45
	v_add_f32_e32 v3, v3, v22
	v_cvt_pk_bf16_f32 v50, v46, v47
	v_cvt_pk_bf16_f32 v51, v48, v49
	v_cvt_pk_f16_f32 v52, v46, v47
	v_cvt_pk_f16_f32 v53, v48, v49
	global_store_dwordx2 v[54:55], v[50:51], off offset:3072
	global_store_dwordx2 v[56:57], v[52:53], off offset:3072
	s_waitcnt vmcnt(14)
	s_nop 1
	v_mov_b64_e32 v[50:51], v[82:83]
	v_mov_b64_e32 v[52:53], v[84:85]
	v_mul_f32_e32 v22, v47, v47
	v_fmac_f32_e32 v22, v46, v46
	v_fmac_f32_e32 v22, v48, v48
	v_fmac_f32_e32 v22, v49, v49
	v_add_f32_e32 v3, v3, v22
	v_mul_f32_e32 v22, v51, v51
	v_fmac_f32_e32 v22, v50, v50
	v_fmac_f32_e32 v22, v52, v52
	v_fmac_f32_e32 v22, v53, v53
	v_add_f32_e32 v3, v3, v22
	ds_bpermute_b32 v22, v16, v3
	v_cvt_pk_bf16_f32 v24, v50, v51
	v_cvt_pk_bf16_f32 v25, v52, v53
	global_store_dwordx2 v[54:55], v[24:25], off offset:3584
	v_cvt_pk_f16_f32 v24, v50, v51
	s_waitcnt lgkmcnt(0)
	v_add_f32_e32 v3, v3, v22
	ds_bpermute_b32 v22, v17, v3
	v_cvt_pk_f16_f32 v25, v52, v53
	global_store_dwordx2 v[56:57], v[24:25], off offset:3584
	s_waitcnt lgkmcnt(0)
	v_add_f32_e32 v3, v3, v22
	ds_bpermute_b32 v22, v18, v3
	s_waitcnt lgkmcnt(0)
	v_add_f32_e32 v3, v3, v22
	ds_bpermute_b32 v22, v19, v3
	s_waitcnt lgkmcnt(0)
	v_add_f32_e32 v3, v3, v22
	ds_bpermute_b32 v22, v20, v3
	s_waitcnt lgkmcnt(0)
	v_add_f32_e32 v3, v3, v22
	ds_bpermute_b32 v22, v21, v3
	s_and_saveexec_b64 s[2:3], s[4:5]
	s_cbranch_execz .LBB0_952
	s_waitcnt lgkmcnt(0)
	v_add_f32_e32 v3, v3, v22
	v_mul_f32_e32 v3, 0x4b800000, v3
	v_rndne_f32_e32 v3, v3
	v_mul_f32_e32 v22, 0x2f800000, v3
	v_floor_f32_e32 v23, v22
	v_fmac_f32_e32 v3, 0xcf800000, v23
	v_cvt_u32_f32_e32 v22, v3
	v_cvt_u32_f32_e32 v23, v23
	v_lshl_add_u64 v[24:25], s[22:23], 0, v[4:5]
	global_store_dwordx2 v[24:25], v[22:23], off
	s_branch .LBB0_952

; __device__ __forceinline__ unsigned cvt_pk_bf16(float lo, float hi) { const f32x2_t v = {lo, hi}; const bf16x2_t b = __builtin_convertvector(v, bf16x2_t); return __builtin_bit_cast(unsigned, b); }
; __device__ __forceinline__ unsigned cvt_pk_f16(float lo, float hi) { const f32x2 v = {lo, hi}; const h16x2_t h = __builtin_convertvector(v, h16x2_t); return __builtin_bit_cast(unsigned, h); }
; __device__ __forceinline__ u64 ssq_fix(float s) { return (u64)__float2ull_rn(s * 16777216.0f); }
; __device__ __forceinline__ void rows_to_bf16(const float* X, bf16_t* XB, bf16_t* X16, u64* ssq, int rows, int gw, int nw) {
;     int tid_ = threadIdx.x; asm volatile("" : "+v"(tid_)); asm volatile("" : "+v"(gw));
;     const int lane = tid_ & 63;
;     for (int r = gw; r < rows; r += nw) {
;         const float* xr = X + (size_t)r * D; bf16_t* br = XB + (size_t)r * D; float ss = 0.f;
; #pragma unroll
;         for (int i = 0; i < 8; ++i) {
;             const f32x4 v = *(const f32x4*)(xr + (i * 64 + lane) * 4);
;             ss += v[0] * v[0] + v[1] * v[1] + v[2] * v[2] + v[3] * v[3];
;             u32x2 w; w.x = cvt_pk_bf16(v[0], v[1]); w.y = cvt_pk_bf16(v[2], v[3]);
;             *(u32x2*)(br + (i * 64 + lane) * 4) = w;
;             if (X16) { u32x2 hq; hq.x = cvt_pk_f16(v[0], v[1]); hq.y = cvt_pk_f16(v[2], v[3]); *(u32x2*)(X16 + (size_t)r * D + (i * 64 + lane) * 4) = hq; }
;         }
;         ss = wave_sum(ss);
;         if (lane == 0) ssq[r] = ssq_fix(ss);
;     }
; }
.LBB0_958:
	s_waitcnt lgkmcnt(0)
	global_load_dwordx4 v[14:17], v[6:7], off offset:-4096 nt
	global_load_dwordx4 v[58:61], v[6:7], off offset:-3072 nt
	global_load_dwordx4 v[62:65], v[6:7], off offset:-2048 nt
	global_load_dwordx4 v[66:69], v[6:7], off offset:-1024 nt
	global_load_dwordx4 v[70:73], v[6:7], off nt
	global_load_dwordx4 v[74:77], v[6:7], off offset:1024 nt
	global_load_dwordx4 v[78:81], v[6:7], off offset:2048 nt
	global_load_dwordx4 v[82:85], v[6:7], off offset:3072 nt
	v_lshl_add_u64 v[18:19], s[22:23], 0, v[4:5]
	s_mov_b32 s2, 0x15a29000
	s_waitcnt vmcnt(18)
	v_add_co_u32_e32 v46, vcc, s2, v18
	s_waitcnt vmcnt(7)
	v_cvt_pk_bf16_f32 v18, v14, v15
	v_addc_co_u32_e32 v47, vcc, 0, v19, vcc
	v_cvt_pk_bf16_f32 v19, v16, v17
	global_store_dwordx2 v[46:47], v[18:19], off
	s_waitcnt vmcnt(7)
	s_nop 1
	v_mov_b64_e32 v[18:19], v[58:59]
	v_mov_b64_e32 v[20:21], v[60:61]
	v_mul_f32_e32 v1, v15, v15
	v_fmac_f32_e32 v1, v14, v14
	v_fmac_f32_e32 v1, v16, v16
	v_fmac_f32_e32 v1, v17, v17
	v_cvt_pk_bf16_f32 v22, v18, v19
	v_cvt_pk_bf16_f32 v23, v20, v21
	global_store_dwordx2 v[46:47], v[22:23], off offset:512
	s_waitcnt vmcnt(7)
	s_nop 1
	v_mov_b64_e32 v[22:23], v[62:63]
	v_mov_b64_e32 v[24:25], v[64:65]
	v_mul_f32_e32 v14, v19, v19
	v_fmac_f32_e32 v14, v18, v18
	v_fmac_f32_e32 v14, v20, v20
	v_fmac_f32_e32 v14, v21, v21
	v_add_f32_e32 v1, v1, v14
	v_cvt_pk_bf16_f32 v26, v22, v23
	v_cvt_pk_bf16_f32 v27, v24, v25
	global_store_dwordx2 v[46:47], v[26:27], off offset:1024
	s_waitcnt vmcnt(7)
	s_nop 1
	v_mov_b64_e32 v[26:27], v[66:67]
	v_mov_b64_e32 v[28:29], v[68:69]
	v_mul_f32_e32 v14, v23, v23
	v_fmac_f32_e32 v14, v22, v22
	v_fmac_f32_e32 v14, v24, v24
	v_fmac_f32_e32 v14, v25, v25
	v_add_f32_e32 v1, v1, v14
	v_cvt_pk_bf16_f32 v30, v26, v27
	v_cvt_pk_bf16_f32 v31, v28, v29
	global_store_dwordx2 v[46:47], v[30:31], off offset:1536
	s_waitcnt vmcnt(7)
	s_nop 1
	v_mov_b64_e32 v[30:31], v[70:71]
	v_mov_b64_e32 v[32:33], v[72:73]
	v_mul_f32_e32 v14, v27, v27
	v_fmac_f32_e32 v14, v26, v26
	v_fmac_f32_e32 v14, v28, v28
	v_fmac_f32_e32 v14, v29, v29
	v_add_f32_e32 v1, v1, v14
	v_cvt_pk_bf16_f32 v34, v30, v31
	v_cvt_pk_bf16_f32 v35, v32, v33
	global_store_dwordx2 v[46:47], v[34:35], off offset:2048
	s_waitcnt vmcnt(7)
	s_nop 1
	v_mov_b64_e32 v[34:35], v[74:75]
	v_mov_b64_e32 v[36:37], v[76:77]
	v_mul_f32_e32 v14, v31, v31
	v_fmac_f32_e32 v14, v30, v30
	v_fmac_f32_e32 v14, v32, v32
	v_fmac_f32_e32 v14, v33, v33
	v_add_f32_e32 v1, v1, v14
	v_cvt_pk_bf16_f32 v38, v34, v35
	v_cvt_pk_bf16_f32 v39, v36, v37
	global_store_dwordx2 v[46:47], v[38:39], off offset:2560
	s_waitcnt vmcnt(7)
	s_nop 1
	v_mov_b64_e32 v[38:39], v[78:79]
	v_mov_b64_e32 v[40:41], v[80:81]
	v_mul_f32_e32 v14, v35, v35
	v_fmac_f32_e32 v14, v34, v34
	v_fmac_f32_e32 v14, v36, v36
	v_fmac_f32_e32 v14, v37, v37
	v_add_f32_e32 v1, v1, v14
	v_cvt_pk_bf16_f32 v42, v38, v39
	v_cvt_pk_bf16_f32 v43, v40, v41
	global_store_dwordx2 v[46:47], v[42:43], off offset:3072
	s_waitcnt vmcnt(7)
	s_nop 1
	v_mov_b64_e32 v[42:43], v[82:83]
	v_mov_b64_e32 v[44:45], v[84:85]
	v_mul_f32_e32 v14, v39, v39
	v_fmac_f32_e32 v14, v38, v38
	v_fmac_f32_e32 v14, v40, v40
	v_fmac_f32_e32 v14, v41, v41
	v_add_f32_e32 v1, v1, v14
	v_mul_f32_e32 v14, v43, v43
	v_fmac_f32_e32 v14, v42, v42
	v_fmac_f32_e32 v14, v44, v44
	v_fmac_f32_e32 v14, v45, v45
	v_add_f32_e32 v1, v1, v14
	ds_bpermute_b32 v14, v8, v1
	v_cvt_pk_bf16_f32 v16, v42, v43
	v_cvt_pk_bf16_f32 v17, v44, v45
	global_store_dwordx2 v[46:47], v[16:17], off offset:3584
	s_waitcnt lgkmcnt(0)
	v_add_f32_e32 v1, v1, v14
	ds_bpermute_b32 v14, v9, v1
	s_waitcnt lgkmcnt(0)
	v_add_f32_e32 v1, v1, v14
	ds_bpermute_b32 v14, v12, v1
	s_waitcnt lgkmcnt(0)
	v_add_f32_e32 v1, v1, v14
	ds_bpermute_b32 v14, v11, v1
	s_waitcnt lgkmcnt(0)
	v_add_f32_e32 v1, v1, v14
	ds_bpermute_b32 v14, v10, v1
	s_waitcnt lgkmcnt(0)
	v_add_f32_e32 v1, v1, v14
	ds_bpermute_b32 v14, v13, v1
	s_and_saveexec_b64 s[2:3], s[4:5]
	s_cbranch_execz .LBB0_957
	s_waitcnt lgkmcnt(0)
	v_add_f32_e32 v1, v1, v14
	v_mul_f32_e32 v1, 0x4b800000, v1
	v_rndne_f32_e32 v1, v1
	v_mul_f32_e32 v14, 0x2f800000, v1
	v_floor_f32_e32 v15, v14
	v_fmac_f32_e32 v1, 0xcf800000, v15
	v_cvt_u32_f32_e32 v14, v1
	v_cvt_u32_f32_e32 v15, v15
	v_lshl_add_u64 v[16:17], s[22:23], 0, v[2:3]
	global_store_dwordx2 v[16:17], v[14:15], off
	s_branch .LBB0_957

; __device__ __forceinline__ f32x2 unpk_f16(unsigned u) { const h16x2_t h = __builtin_bit_cast(h16x2_t, u); return __builtin_convertvector(h, f32x2); }
; __device__ __forceinline__ float rstd_of(u64 ssq) { return frsq((float)ssq * (1.0f / (2048.0f * 16777216.0f)) + EPS); }
; __global__ void __launch_bounds__(NTHREADS, 2) fwd_kernel(Args a) {
;     ...
;             for (int r = gw; r < T; r += nw) {
;                 const float rs = rstd_of(ssq[r]); const bf16_t* hr = (const bf16_t*)(ws + WS_H16) + (size_t)r * D; float* orow = out + (size_t)r * D;
; #pragma unroll
;                 for (int i = 0; i < 8; ++i) { const int cidx = (i * 64 + lane) * 4; const u32x2 hw = *(const u32x2*)(hr + cidx); const f32x4 gg = *(const f32x4*)(fg + cidx);
;                     const f32x2 a2 = unpk_f16(hw.x), b2 = unpk_f16(hw.y); f32x4 v; v[0] = a2.x; v[1] = a2.y; v[2] = b2.x; v[3] = b2.y; *(f32x4*)(orow + cidx) = v * rs * gg; }
;             }
.LBB0_964:
	global_load_dwordx2 v[22:23], v[10:11], off nt
	global_load_dwordx2 v[24:25], v[14:15], off offset:-2048 nt
	global_load_dwordx4 v[18:21], v[0:1], off nt
	global_load_dwordx2 v[58:59], v[14:15], off offset:-1536 nt
	global_load_dwordx4 v[60:63], v[0:1], off offset:1024 nt
	global_load_dwordx2 v[64:65], v[14:15], off offset:-1024 nt
	global_load_dwordx4 v[66:69], v[0:1], off offset:2048 nt
	global_load_dwordx2 v[70:71], v[14:15], off offset:-512 nt
	global_load_dwordx4 v[72:75], v[0:1], off offset:3072 nt
	global_load_dwordx2 v[76:77], v[14:15], off nt
	global_load_dwordx4 v[78:81], v[2:3], off nt
	global_load_dwordx2 v[82:83], v[14:15], off offset:512 nt
	global_load_dwordx4 v[84:87], v[4:5], off nt
	global_load_dwordx2 v[88:89], v[14:15], off offset:1024 nt
	global_load_dwordx4 v[90:93], v[6:7], off nt
	global_load_dwordx2 v[94:95], v[14:15], off offset:1536 nt
	global_load_dwordx4 v[96:99], v[8:9], off nt
	s_movk_i32 s2, 0xf000
	v_add_co_u32_e32 v26, vcc, s2, v12
	v_add_u32_e32 v16, s6, v16
	s_nop 0
	v_addc_co_u32_e32 v27, vcc, -1, v13, vcc
	v_cmp_lt_i32_e32 vcc, s36, v16
	v_lshl_add_u64 v[10:11], v[10:11], 0, s[8:9]
	s_or_b64 s[14:15], vcc, s[14:15]
	s_waitcnt vmcnt(16)
	v_ffbh_u32_e32 v17, v23
	v_min_u32_e32 v17, 32, v17
	v_lshlrev_b64 v[22:23], v17, v[22:23]
	v_min_u32_e32 v22, 1, v22
	v_or_b32_e32 v22, v23, v22
	v_cvt_f32_u32_e32 v22, v22
	v_sub_u32_e32 v17, 32, v17
	s_waitcnt vmcnt(15)
	v_cvt_f32_f16_sdwa v29, v24 dst_sel:DWORD dst_unused:UNUSED_PAD src0_sel:WORD_1
	v_cvt_f32_f16_e32 v28, v24
	v_ldexp_f32 v17, v22, v17
	v_fmamk_f32 v17, v17, 0x2e000000, v239
	v_cvt_f32_f16_sdwa v31, v25 dst_sel:DWORD dst_unused:UNUSED_PAD src0_sel:WORD_1
	v_cvt_f32_f16_e32 v30, v25
	v_rsq_f32_e32 v22, v17
	s_nop 0
	v_pk_mul_f32 v[24:25], v[22:23], v[28:29] op_sel_hi:[0,1]
	v_pk_mul_f32 v[28:29], v[22:23], v[30:31] op_sel_hi:[0,1]
	s_waitcnt vmcnt(14)
	v_pk_mul_f32 v[20:21], v[20:21], v[28:29]
	v_pk_mul_f32 v[18:19], v[18:19], v[24:25]
	global_store_dwordx4 v[26:27], v[18:21], off offset:-3072
	s_waitcnt vmcnt(14)
	s_nop 1
	v_mov_b64_e32 v[24:25], v[58:59]
	s_nop 0
	s_waitcnt vmcnt(13)
	s_nop 1
	v_mov_b64_e32 v[18:19], v[60:61]
	v_mov_b64_e32 v[20:21], v[62:63]
	v_cvt_f32_f16_sdwa v29, v24 dst_sel:DWORD dst_unused:UNUSED_PAD src0_sel:WORD_1
	v_cvt_f32_f16_e32 v28, v24
	v_cvt_f32_f16_sdwa v31, v25 dst_sel:DWORD dst_unused:UNUSED_PAD src0_sel:WORD_1
	v_cvt_f32_f16_e32 v30, v25
	v_pk_mul_f32 v[24:25], v[22:23], v[28:29] op_sel_hi:[0,1]
	v_pk_mul_f32 v[18:19], v[18:19], v[24:25]
	v_pk_mul_f32 v[28:29], v[22:23], v[30:31] op_sel_hi:[0,1]
	v_pk_mul_f32 v[20:21], v[20:21], v[28:29]
	global_store_dwordx4 v[26:27], v[18:21], off offset:-2048
	s_waitcnt vmcnt(13)
	s_nop 1
	v_mov_b64_e32 v[24:25], v[64:65]
	s_nop 0
	s_waitcnt vmcnt(12)
	s_nop 1
	v_mov_b64_e32 v[18:19], v[66:67]
	v_mov_b64_e32 v[20:21], v[68:69]
	v_cvt_f32_f16_sdwa v29, v24 dst_sel:DWORD dst_unused:UNUSED_PAD src0_sel:WORD_1
	v_cvt_f32_f16_e32 v28, v24
	v_cvt_f32_f16_sdwa v31, v25 dst_sel:DWORD dst_unused:UNUSED_PAD src0_sel:WORD_1
	v_cvt_f32_f16_e32 v30, v25
	v_pk_mul_f32 v[24:25], v[22:23], v[28:29] op_sel_hi:[0,1]
	v_pk_mul_f32 v[18:19], v[18:19], v[24:25]
	v_pk_mul_f32 v[28:29], v[22:23], v[30:31] op_sel_hi:[0,1]
	v_pk_mul_f32 v[20:21], v[20:21], v[28:29]
	global_store_dwordx4 v[26:27], v[18:21], off offset:-1024
	s_waitcnt vmcnt(12)
	s_nop 1
	v_mov_b64_e32 v[24:25], v[70:71]
	s_nop 0
	s_waitcnt vmcnt(11)
	s_nop 1
	v_mov_b64_e32 v[18:19], v[72:73]
	v_mov_b64_e32 v[20:21], v[74:75]
	v_cvt_f32_f16_sdwa v27, v24 dst_sel:DWORD dst_unused:UNUSED_PAD src0_sel:WORD_1
	v_cvt_f32_f16_e32 v26, v24
	v_cvt_f32_f16_sdwa v29, v25 dst_sel:DWORD dst_unused:UNUSED_PAD src0_sel:WORD_1
	v_cvt_f32_f16_e32 v28, v25
	v_pk_mul_f32 v[24:25], v[22:23], v[26:27] op_sel_hi:[0,1]
	v_pk_mul_f32 v[18:19], v[18:19], v[24:25]
	v_pk_mul_f32 v[26:27], v[22:23], v[28:29] op_sel_hi:[0,1]
	v_pk_mul_f32 v[20:21], v[20:21], v[26:27]
	global_store_dwordx4 v[12:13], v[18:21], off offset:-4096
	s_waitcnt vmcnt(11)
	s_nop 1
	v_mov_b64_e32 v[24:25], v[76:77]
	s_nop 0
	s_waitcnt vmcnt(10)
	s_nop 1
	v_mov_b64_e32 v[18:19], v[78:79]
	v_mov_b64_e32 v[20:21], v[80:81]
	v_cvt_f32_f16_sdwa v27, v24 dst_sel:DWORD dst_unused:UNUSED_PAD src0_sel:WORD_1
	v_cvt_f32_f16_e32 v26, v24
	v_cvt_f32_f16_sdwa v29, v25 dst_sel:DWORD dst_unused:UNUSED_PAD src0_sel:WORD_1
	v_cvt_f32_f16_e32 v28, v25
	v_pk_mul_f32 v[24:25], v[22:23], v[26:27] op_sel_hi:[0,1]
	v_pk_mul_f32 v[18:19], v[18:19], v[24:25]
	v_pk_mul_f32 v[26:27], v[22:23], v[28:29] op_sel_hi:[0,1]
	v_pk_mul_f32 v[20:21], v[20:21], v[26:27]
	global_store_dwordx4 v[12:13], v[18:21], off offset:-3072
	s_waitcnt vmcnt(10)
	s_nop 1
	v_mov_b64_e32 v[24:25], v[82:83]
	s_nop 0
	s_waitcnt vmcnt(9)
	s_nop 1
	v_mov_b64_e32 v[18:19], v[84:85]
	v_mov_b64_e32 v[20:21], v[86:87]
	v_cvt_f32_f16_sdwa v27, v24 dst_sel:DWORD dst_unused:UNUSED_PAD src0_sel:WORD_1
	v_cvt_f32_f16_e32 v26, v24
	v_cvt_f32_f16_sdwa v29, v25 dst_sel:DWORD dst_unused:UNUSED_PAD src0_sel:WORD_1
	v_cvt_f32_f16_e32 v28, v25
	v_pk_mul_f32 v[24:25], v[22:23], v[26:27] op_sel_hi:[0,1]
	v_pk_mul_f32 v[18:19], v[18:19], v[24:25]
	v_pk_mul_f32 v[26:27], v[22:23], v[28:29] op_sel_hi:[0,1]
	v_pk_mul_f32 v[20:21], v[20:21], v[26:27]
	global_store_dwordx4 v[12:13], v[18:21], off offset:-2048
	s_waitcnt vmcnt(9)
	s_nop 1
	v_mov_b64_e32 v[24:25], v[88:89]
	s_nop 0
	s_waitcnt vmcnt(8)
	s_nop 1
	v_mov_b64_e32 v[18:19], v[90:91]
	v_mov_b64_e32 v[20:21], v[92:93]
	v_cvt_f32_f16_sdwa v27, v24 dst_sel:DWORD dst_unused:UNUSED_PAD src0_sel:WORD_1
	v_cvt_f32_f16_e32 v26, v24
	v_cvt_f32_f16_sdwa v29, v25 dst_sel:DWORD dst_unused:UNUSED_PAD src0_sel:WORD_1
	v_cvt_f32_f16_e32 v28, v25
	v_pk_mul_f32 v[24:25], v[22:23], v[26:27] op_sel_hi:[0,1]
	v_pk_mul_f32 v[18:19], v[18:19], v[24:25]
	v_pk_mul_f32 v[26:27], v[22:23], v[28:29] op_sel_hi:[0,1]
	v_pk_mul_f32 v[20:21], v[20:21], v[26:27]
	global_store_dwordx4 v[12:13], v[18:21], off offset:-1024
	s_waitcnt vmcnt(8)
	s_nop 1
	v_mov_b64_e32 v[24:25], v[94:95]
	s_nop 0
	s_waitcnt vmcnt(7)
	s_nop 1
	v_mov_b64_e32 v[18:19], v[96:97]
	v_mov_b64_e32 v[20:21], v[98:99]
	v_lshl_add_u64 v[14:15], v[14:15], 0, s[12:13]
	v_cvt_f32_f16_sdwa v27, v24 dst_sel:DWORD dst_unused:UNUSED_PAD src0_sel:WORD_1
	v_cvt_f32_f16_e32 v26, v24
	v_cvt_f32_f16_sdwa v29, v25 dst_sel:DWORD dst_unused:UNUSED_PAD src0_sel:WORD_1
	v_cvt_f32_f16_e32 v28, v25
	v_pk_mul_f32 v[24:25], v[22:23], v[26:27] op_sel_hi:[0,1]
	v_pk_mul_f32 v[18:19], v[18:19], v[24:25]
	v_pk_mul_f32 v[22:23], v[22:23], v[28:29] op_sel_hi:[0,1]
	v_pk_mul_f32 v[20:21], v[20:21], v[22:23]
	global_store_dwordx4 v[12:13], v[18:21], off
	v_lshl_add_u64 v[12:13], v[12:13], 0, s[10:11]
	s_andn2_b64 exec, exec, s[14:15]
	s_cbranch_execnz .LBB0_964
